# P7 full unit: last K iteration's A-type dummy staging loads become an L2 prefetch of the H1B residual tile (one line per lane)
# baseline (speedup 1.0000x reference)
; #define PG8_LAS __attribute__((address_space(3)))
;     __device__ __forceinline__ void fused(f32x4 (&acc)[2][2][4][2], const Unit& u, int wr, int wc, int fr, int fq, PG8_LAS unsigned char* lds, int wid, int lane) const {
;     ...
;         for (int j = 0; j < 16; ++j) {
;             const int rA = wid * 32 + 2 * j, rl = rA + (lane >> 5), chunk = ((lane & 31) + rl) & 31;
;             const bf16_t* src = h1b + (size_t)(u.pm * BM + rl) * DM + u.pn * BM + chunk * 8;
;             __builtin_amdgcn_global_load_lds((const unsigned*)src, (PG8_LAS unsigned*)(lds + rA * 512), 16, 0, 2);
;     ...
;             const char* a1 = cA + (size_t)(t + 1) * kstep;
;             const char* a2 = last ? nA : cA + (size_t)(t + 2) * kstep; const char* b2 = last ? nB : cB + (size_t)(t + 2) * kstep;
;             const char* a3 = a2 + kstep; const char* b3 = b2 + kstep;
.Lp7r_do:
	s_cmp_eq_u32 s101, 0
	s_cbranch_scc1 .Lp7r_back
	v_readlane_b32 s98, v255, 13
	v_mbcnt_lo_u32_b32 v134, -1, 0
	v_mbcnt_hi_u32_b32 v134, -1, v134
	s_lshl_b32 s98, s98, 16
	v_and_b32_e32 v135, 3, v134
	v_lshrrev_b32_e32 v134, 2, v134
	v_lshl_add_u32 v134, v134, 11, s98
	v_lshl_add_u32 v134, v135, 7, v134
	v_add_u32_e32 v138, 0x8000, v134
	v_mov_b32_e32 v135, 0
	v_mov_b32_e32 v139, 0
	s_branch .Lp7r_back

; #define PG8_STAGE(bufoff, gbase, voff) do { _Pragma("unroll") for (int _i = 0; _i < 2; ++_i) \
;         __builtin_amdgcn_global_load_lds((const unsigned*)((const char*)(gbase) + (voff)[_i]), (PG8_LAS unsigned*)(lds + (bufoff) + ldsw + _i * 8192), 16, 0, 0); } while (0)
; #define PG8_STAGEA(bufoff, gbase, voff) do { _Pragma("unroll") for (int _i = 0; _i < 2; ++_i) \
;         __builtin_amdgcn_global_load_lds((const unsigned*)((const char*)(gbase) + (voff)[_i]), (PG8_LAS unsigned*)(lds + (bufoff) + ldsw + _i * 8192), 16, 0, AUXA); } while (0)
; #define PG8_LDA(dst, b, h) do { _Pragma("unroll") for (int m = 0; m < 4; ++m) _Pragma("unroll") for (int k = 0; k < 2; ++k) dst[m][k] = *(const PG8_LAS bf16x8*)(lds + PG8_SA(b, h) + aoff + m * 2048 + k * 1024); } while (0)
; #define PG8_LDB(dst, b, h) do { _Pragma("unroll") for (int n = 0; n < 2; ++n) _Pragma("unroll") for (int k = 0; k < 2; ++k) dst[n][k] = *(const PG8_LAS bf16x8*)(lds + PG8_SB(b, h) + boff + n * 2048 + k * 1024); } while (0)
; #define PG8_WAIT_V(n) asm volatile("s_waitcnt vmcnt(" #n ")" ::: "memory")
; #define PG8_WAIT_L(n) asm volatile("s_waitcnt lgkmcnt(" #n ")" ::: "memory")
; #define PG8_BAR __builtin_amdgcn_s_barrier()
; #define PG8_SCHED __builtin_amdgcn_sched_barrier(0)
;     ...
;         const char* nA = has_next ? (const char*)g.A + (size_t)nxt.pm * tstep + (size_t)nxt.k0 * (BK * 2) : cA; const char* nB = has_next ? (const char*)g.Bt + (size_t)nxt.pn * tstep + (size_t)nxt.k0 * (BK * 2) : cB;
;         const int nt = cur.nt;
;         for (int t = 0; t < nt; t += 2) {
;             const bool last = (t == nt - 2);
;             const char* a1 = cA + (size_t)(t + 1) * kstep;
;             const char* a2 = last ? nA : cA + (size_t)(t + 2) * kstep; const char* b2 = last ? nB : cB + (size_t)(t + 2) * kstep;
;             const char* a3 = a2 + kstep; const char* b3 = b2 + kstep;
;             if (last && has_next) S.a_ready(nxt);
;             if constexpr (SP2) {
;             PG8_LDB(B0, 0, 0); PG8_LDB(B1, 0, 1); PG8_SCHED; PG8_LDA(At, 0, 0); PG8_STAGEA(PG8_SA(1, 1), a1 + hstep, voffA);
;             PG8_WAIT_V(8); PG8_WAIT_L(0); PG8_BAR; PG8_MMA(0, 0, At, B0); PG8_MMA(0, 1, At, B1); PG8_BAR; PG8_SCHED;
;             PG8_LDA(At, 0, 1); PG8_STAGE(PG8_SB(0, 0), b2, voffB); PG8_STAGE(PG8_SB(0, 1), b2 + hstepB, voffB); PG8_STAGEA(PG8_SA(0, 0), a2, voffA);
.LBB0_1053:
	s_ashr_i32 s23, s22, 31
	s_xor_b64 s[28:29], s[40:41], -1
	s_lshl_b64 s[30:31], s[22:23], 21
	s_add_u32 s13, s4, s30
	s_addc_u32 s23, s5, s31
	s_ashr_i32 s27, s26, 31
	s_lshl_b64 s[34:35], s[26:27], 7
	s_add_u32 s30, s13, s34
	s_addc_u32 s31, s23, s35
	s_and_b64 s[42:43], s[40:41], exec
	s_cselect_b32 s13, s31, s39
	s_cselect_b32 s23, s30, s38
	s_ashr_i32 s25, s24, 31
	s_lshl_b64 s[42:43], s[24:25], 21
	s_add_u32 s25, s3, s42
	s_addc_u32 s27, s47, s43
	s_add_u32 s34, s25, s34
	s_addc_u32 s35, s27, s35
	s_and_b64 s[42:43], s[40:41], exec
	s_cselect_b32 s25, s35, s37
	s_cselect_b32 s27, s34, s36
	s_sub_u32 s98, s38, s4
	s_lshr_b32 s98, s98, 2
	s_sub_u32 s99, s36, s3
	s_lshr_b32 s99, s99, 12
	s_add_u32 s98, s98, s99
	s_add_u32 s98, s98, 0xdc00000
	s_add_u32 s98, s68, s98
	s_addc_u32 s99, s69, 0
	s_and_b64 s[42:43], s[40:41], exec
	s_cselect_b32 s23, s23, s98
	s_cselect_b32 s13, s13, s99
	s_cselect_b32 s101, 0, 1
	s_mov_b32 s73, 2
	s_mov_b64 s[42:43], 0x100
	v_mov_b64_e32 v[130:131], v[144:145]
	v_mov_b64_e32 v[150:151], v[142:143]
	v_readlane_b32 s98, v255, 17
	s_cmp_lg_u32 s98, 1
	s_cbranch_scc1 .Lsprio_6
	s_setprio 1
.Lsprio_6:
.LBB0_1054:
	v_add_u32_e32 v128, s59, v163
	ds_read_b128 v[166:169], v128
	ds_read_b128 v[170:173], v128 offset:1024
	ds_read_b128 v[176:179], v128 offset:2048
	ds_read_b128 v[180:183], v128 offset:3072
	v_add_u32_e32 v128, s70, v163
	ds_read_b128 v[184:187], v128
	ds_read_b128 v[188:191], v128 offset:1024
	ds_read_b128 v[192:195], v128 offset:2048
	ds_read_b128 v[196:199], v128 offset:3072
	s_add_u32 s44, s38, s42
	s_addc_u32 s45, s39, s43
	s_add_u32 s74, s36, s42
	s_addc_u32 s75, s37, s43
	s_cmp_eq_u32 s57, s73
	s_cselect_b32 s51, s13, s45
	s_cselect_b32 s50, s23, s44
	s_cselect_b32 s45, s25, s75
	s_cselect_b32 s44, s27, s74
	s_cbranch_scc1 .Lp7r_do
.Lp7r_back:
	v_lshl_add_u64 v[206:207], s[38:39], 0, v[150:151]
	s_add_i32 m0, s49, 0xc000
	ds_read_b128 v[202:205], v164
	ds_read_b128 v[210:213], v164 offset:1024
	ds_read_b128 v[214:217], v164 offset:2048
	ds_read_b128 v[218:221], v164 offset:3072
	ds_read_b128 v[222:225], v164 offset:4096
	ds_read_b128 v[226:229], v164 offset:5120
	ds_read_b128 v[230:233], v164 offset:6144
	ds_read_b128 v[234:237], v164 offset:7168
	global_load_lds_dwordx4 v[206:207], off
	v_lshl_add_u64 v[206:207], s[38:39], 0, v[130:131]
	s_add_i32 m0, s49, 0xe000
	s_nop 0
	global_load_lds_dwordx4 v[206:207], off
	s_waitcnt vmcnt(8)
	s_waitcnt lgkmcnt(0)
	s_barrier
	s_waitcnt lgkmcnt(0)
	v_mfma_f32_16x16x32_bf16 v[124:127], v[166:169], v[202:205], v[124:127]
	v_mfma_f32_16x16x32_bf16 v[120:123], v[176:179], v[202:205], v[120:123]
	v_mfma_f32_16x16x32_bf16 v[108:111], v[166:169], v[214:217], v[108:111]
	v_mfma_f32_16x16x32_bf16 v[104:107], v[176:179], v[214:217], v[104:107]
	v_mfma_f32_16x16x32_bf16 v[92:95], v[166:169], v[222:225], v[92:95]
	v_mfma_f32_16x16x32_bf16 v[88:91], v[176:179], v[222:225], v[88:91]
	v_mfma_f32_16x16x32_bf16 v[76:79], v[166:169], v[230:233], v[76:79]
	v_mfma_f32_16x16x32_bf16 v[72:75], v[176:179], v[230:233], v[72:75]
	v_mfma_f32_16x16x32_bf16 v[124:127], v[170:173], v[210:213], v[124:127]
	v_mfma_f32_16x16x32_bf16 v[120:123], v[180:183], v[210:213], v[120:123]
	v_mfma_f32_16x16x32_bf16 v[108:111], v[170:173], v[218:221], v[108:111]
	v_mfma_f32_16x16x32_bf16 v[104:107], v[180:183], v[218:221], v[104:107]
	v_mfma_f32_16x16x32_bf16 v[92:95], v[170:173], v[226:229], v[92:95]
	v_mfma_f32_16x16x32_bf16 v[88:91], v[180:183], v[226:229], v[88:91]
	v_mfma_f32_16x16x32_bf16 v[76:79], v[170:173], v[234:237], v[76:79]
	v_mfma_f32_16x16x32_bf16 v[72:75], v[180:183], v[234:237], v[72:75]
	v_mfma_f32_16x16x32_bf16 v[116:119], v[184:187], v[202:205], v[116:119]
	v_mfma_f32_16x16x32_bf16 v[112:115], v[192:195], v[202:205], v[112:115]
	v_mfma_f32_16x16x32_bf16 v[100:103], v[184:187], v[214:217], v[100:103]
	v_mfma_f32_16x16x32_bf16 v[96:99], v[192:195], v[214:217], v[96:99]
	v_mfma_f32_16x16x32_bf16 v[84:87], v[184:187], v[222:225], v[84:87]
	v_mfma_f32_16x16x32_bf16 v[80:83], v[192:195], v[222:225], v[80:83]
	v_mfma_f32_16x16x32_bf16 v[68:71], v[184:187], v[230:233], v[68:71]
	v_mfma_f32_16x16x32_bf16 v[64:67], v[192:195], v[230:233], v[64:67]
	v_mfma_f32_16x16x32_bf16 v[116:119], v[188:191], v[210:213], v[116:119]
	v_mfma_f32_16x16x32_bf16 v[112:115], v[196:199], v[210:213], v[112:115]
	v_mfma_f32_16x16x32_bf16 v[100:103], v[188:191], v[218:221], v[100:103]
	v_mfma_f32_16x16x32_bf16 v[96:99], v[196:199], v[218:221], v[96:99]
	v_mfma_f32_16x16x32_bf16 v[84:87], v[188:191], v[226:229], v[84:87]
	v_mfma_f32_16x16x32_bf16 v[80:83], v[196:199], v[226:229], v[80:83]
	v_mfma_f32_16x16x32_bf16 v[68:71], v[188:191], v[234:237], v[68:71]
	v_mfma_f32_16x16x32_bf16 v[64:67], v[196:199], v[234:237], v[64:67]
	s_barrier
	s_add_i32 s74, s59, s67
	v_lshl_add_u64 v[206:207], s[44:45], 0, v[136:137]
	s_mov_b32 m0, s74
	ds_read_b128 v[202:205], v164 offset:16384
	ds_read_b128 v[210:213], v164 offset:17408
	ds_read_b128 v[214:217], v164 offset:18432
	ds_read_b128 v[218:221], v164 offset:19456
	ds_read_b128 v[222:225], v164 offset:20480
	ds_read_b128 v[226:229], v164 offset:21504
	ds_read_b128 v[230:233], v164 offset:22528
	ds_read_b128 v[234:237], v164 offset:23552
	global_load_lds_dwordx4 v[206:207], off
	s_add_i32 m0, s74, 0x2000
	s_add_u32 s74, s44, 0x40000
	v_lshl_add_u64 v[238:239], s[44:45], 0, v[140:141]
	s_addc_u32 s75, s45, 0
	s_add_i32 s76, s70, s67
	global_load_lds_dwordx4 v[238:239], off
	v_lshl_add_u64 v[240:241], s[74:75], 0, v[136:137]
	s_mov_b32 m0, s76
	v_lshl_add_u64 v[242:243], s[50:51], 0, v[138:139]
	global_load_lds_dwordx4 v[240:241], off
	v_lshl_add_u64 v[240:241], s[74:75], 0, v[140:141]
	s_add_i32 m0, s76, 0x2000
	s_nop 0
	global_load_lds_dwordx4 v[240:241], off
	v_lshl_add_u64 v[240:241], s[50:51], 0, v[134:135]
	s_mov_b32 m0, s49
	s_nop 0
	global_load_lds_dwordx4 v[240:241], off
	s_mov_b32 m0, s52
	s_nop 0
	global_load_lds_dwordx4 v[242:243], off
	s_waitcnt vmcnt(8)
	s_waitcnt lgkmcnt(0)
	s_barrier
; #define PG8_STAGEA(bufoff, gbase, voff) do { _Pragma("unroll") for (int _i = 0; _i < 2; ++_i) \
;         __builtin_amdgcn_global_load_lds((const unsigned*)((const char*)(gbase) + (voff)[_i]), (PG8_LAS unsigned*)(lds + (bufoff) + ldsw + _i * 8192), 16, 0, AUXA); } while (0)
; #define PG8_LDA(dst, b, h) do { _Pragma("unroll") for (int m = 0; m < 4; ++m) _Pragma("unroll") for (int k = 0; k < 2; ++k) dst[m][k] = *(const PG8_LAS bf16x8*)(lds + PG8_SA(b, h) + aoff + m * 2048 + k * 1024); } while (0)
; #define PG8_LDB(dst, b, h) do { _Pragma("unroll") for (int n = 0; n < 2; ++n) _Pragma("unroll") for (int k = 0; k < 2; ++k) dst[n][k] = *(const PG8_LAS bf16x8*)(lds + PG8_SB(b, h) + boff + n * 2048 + k * 1024); } while (0)
; #define PG8_MMA(ai, bj, At, Bt) do { __builtin_amdgcn_s_setprio(1); _Pragma("unroll") for (int m = 0; m < 4; ++m) _Pragma("unroll") for (int n = 0; n < 2; ++n) _Pragma("unroll") for (int k = 0; k < 2; ++k) \
;         acc[ai][bj][m][n] = __builtin_amdgcn_mfma_f32_16x16x32_bf16(Bt[n][k], At[m][k], acc[ai][bj][m][n], 0, 0, 0); __builtin_amdgcn_s_setprio(0); } while (0)
; #define PG8_WAIT_V(n) asm volatile("s_waitcnt vmcnt(" #n ")" ::: "memory")
; #define PG8_WAIT_L(n) asm volatile("s_waitcnt lgkmcnt(" #n ")" ::: "memory")
; #define PG8_BAR __builtin_amdgcn_s_barrier()
; #define PG8_SCHED __builtin_amdgcn_sched_barrier(0)
;     ...
;             PG8_WAIT_V(8); PG8_WAIT_L(0); PG8_BAR; PG8_MMA(1, 0, At, B0); PG8_MMA(1, 1, At, B1); PG8_BAR; PG8_SCHED;
;             PG8_LDB(B0, 1, 0); PG8_LDB(B1, 1, 1); PG8_SCHED; PG8_LDA(At, 1, 0); PG8_STAGEA(PG8_SA(0, 1), a2 + hstep, voffA);
;             PG8_WAIT_V(8); PG8_WAIT_L(0); PG8_BAR; PG8_MMA(0, 0, At, B0); PG8_MMA(0, 1, At, B1); PG8_BAR; PG8_SCHED;
	s_waitcnt lgkmcnt(0)
	v_mfma_f32_16x16x32_bf16 v[60:63], v[166:169], v[202:205], v[60:63]
	v_mfma_f32_16x16x32_bf16 v[56:59], v[176:179], v[202:205], v[56:59]
	v_mfma_f32_16x16x32_bf16 v[44:47], v[166:169], v[214:217], v[44:47]
	v_mfma_f32_16x16x32_bf16 v[40:43], v[176:179], v[214:217], v[40:43]
	v_mfma_f32_16x16x32_bf16 v[28:31], v[166:169], v[222:225], v[28:31]
	v_mfma_f32_16x16x32_bf16 v[24:27], v[176:179], v[222:225], v[24:27]
	v_mfma_f32_16x16x32_bf16 v[12:15], v[166:169], v[230:233], v[12:15]
	v_mfma_f32_16x16x32_bf16 v[8:11], v[176:179], v[230:233], v[8:11]
	v_mfma_f32_16x16x32_bf16 v[60:63], v[170:173], v[210:213], v[60:63]
	v_mfma_f32_16x16x32_bf16 v[56:59], v[180:183], v[210:213], v[56:59]
	v_mfma_f32_16x16x32_bf16 v[44:47], v[170:173], v[218:221], v[44:47]
	v_mfma_f32_16x16x32_bf16 v[40:43], v[180:183], v[218:221], v[40:43]
	v_mfma_f32_16x16x32_bf16 v[28:31], v[170:173], v[226:229], v[28:31]
	v_mfma_f32_16x16x32_bf16 v[24:27], v[180:183], v[226:229], v[24:27]
	v_mfma_f32_16x16x32_bf16 v[12:15], v[170:173], v[234:237], v[12:15]
	v_mfma_f32_16x16x32_bf16 v[8:11], v[180:183], v[234:237], v[8:11]
	v_mfma_f32_16x16x32_bf16 v[52:55], v[184:187], v[202:205], v[52:55]
	v_mfma_f32_16x16x32_bf16 v[48:51], v[192:195], v[202:205], v[48:51]
	v_mfma_f32_16x16x32_bf16 v[36:39], v[184:187], v[214:217], v[36:39]
	v_mfma_f32_16x16x32_bf16 v[32:35], v[192:195], v[214:217], v[32:35]
	v_mfma_f32_16x16x32_bf16 v[20:23], v[184:187], v[222:225], v[20:23]
	v_mfma_f32_16x16x32_bf16 v[16:19], v[192:195], v[222:225], v[16:19]
	v_mfma_f32_16x16x32_bf16 v[4:7], v[184:187], v[230:233], v[4:7]
	v_mfma_f32_16x16x32_bf16 v[0:3], v[192:195], v[230:233], v[0:3]
	v_mfma_f32_16x16x32_bf16 v[52:55], v[188:191], v[210:213], v[52:55]
	v_mfma_f32_16x16x32_bf16 v[48:51], v[196:199], v[210:213], v[48:51]
	v_mfma_f32_16x16x32_bf16 v[36:39], v[188:191], v[218:221], v[36:39]
	v_mfma_f32_16x16x32_bf16 v[32:35], v[196:199], v[218:221], v[32:35]
	v_mfma_f32_16x16x32_bf16 v[20:23], v[188:191], v[226:229], v[20:23]
	v_mfma_f32_16x16x32_bf16 v[16:19], v[196:199], v[226:229], v[16:19]
	v_mfma_f32_16x16x32_bf16 v[4:7], v[188:191], v[234:237], v[4:7]
	v_mfma_f32_16x16x32_bf16 v[0:3], v[196:199], v[234:237], v[0:3]
	s_barrier
	s_add_i32 s74, 0, 0x18000
	v_add_u32_e32 v128, s74, v163
	s_add_i32 s75, 0, 0x1c000
	ds_read_b128 v[166:169], v128
	ds_read_b128 v[170:173], v128 offset:1024
	ds_read_b128 v[176:179], v128 offset:2048
	ds_read_b128 v[180:183], v128 offset:3072
	v_add_u32_e32 v128, s75, v163
	ds_read_b128 v[184:187], v128
	ds_read_b128 v[188:191], v128 offset:1024
	ds_read_b128 v[192:195], v128 offset:2048
	ds_read_b128 v[196:199], v128 offset:3072
	s_add_u32 s50, s50, 0x100000
	s_addc_u32 s51, s51, 0
	s_mov_b32 m0, s53
	v_lshl_add_u64 v[244:245], s[50:51], 0, v[134:135]
	ds_read_b128 v[202:205], v164 offset:32768
	ds_read_b128 v[210:213], v164 offset:33792
	ds_read_b128 v[214:217], v164 offset:34816
	ds_read_b128 v[218:221], v164 offset:35840
	ds_read_b128 v[222:225], v164 offset:36864
	ds_read_b128 v[226:229], v164 offset:37888
	ds_read_b128 v[230:233], v164 offset:38912
	ds_read_b128 v[234:237], v164 offset:39936
	global_load_lds_dwordx4 v[244:245], off
	v_lshl_add_u64 v[244:245], s[50:51], 0, v[138:139]
	s_mov_b32 m0, s54
	s_nop 0
	global_load_lds_dwordx4 v[244:245], off
	s_waitcnt vmcnt(8)
	s_waitcnt lgkmcnt(0)
	s_barrier
	s_waitcnt lgkmcnt(0)
	v_mfma_f32_16x16x32_bf16 v[124:127], v[166:169], v[202:205], v[124:127]
	v_mfma_f32_16x16x32_bf16 v[120:123], v[176:179], v[202:205], v[120:123]
	v_mfma_f32_16x16x32_bf16 v[108:111], v[166:169], v[214:217], v[108:111]
	v_mfma_f32_16x16x32_bf16 v[104:107], v[176:179], v[214:217], v[104:107]
	v_mfma_f32_16x16x32_bf16 v[92:95], v[166:169], v[222:225], v[92:95]
	v_mfma_f32_16x16x32_bf16 v[88:91], v[176:179], v[222:225], v[88:91]
	v_mfma_f32_16x16x32_bf16 v[76:79], v[166:169], v[230:233], v[76:79]
	v_mfma_f32_16x16x32_bf16 v[72:75], v[176:179], v[230:233], v[72:75]
	v_mfma_f32_16x16x32_bf16 v[124:127], v[170:173], v[210:213], v[124:127]
	v_mfma_f32_16x16x32_bf16 v[120:123], v[180:183], v[210:213], v[120:123]
	v_mfma_f32_16x16x32_bf16 v[108:111], v[170:173], v[218:221], v[108:111]
	v_mfma_f32_16x16x32_bf16 v[104:107], v[180:183], v[218:221], v[104:107]
	v_mfma_f32_16x16x32_bf16 v[92:95], v[170:173], v[226:229], v[92:95]
	v_mfma_f32_16x16x32_bf16 v[88:91], v[180:183], v[226:229], v[88:91]
	v_mfma_f32_16x16x32_bf16 v[76:79], v[170:173], v[234:237], v[76:79]
	v_mfma_f32_16x16x32_bf16 v[72:75], v[180:183], v[234:237], v[72:75]
	v_mfma_f32_16x16x32_bf16 v[116:119], v[184:187], v[202:205], v[116:119]
	v_mfma_f32_16x16x32_bf16 v[112:115], v[192:195], v[202:205], v[112:115]
	v_mfma_f32_16x16x32_bf16 v[100:103], v[184:187], v[214:217], v[100:103]
	v_mfma_f32_16x16x32_bf16 v[96:99], v[192:195], v[214:217], v[96:99]
	v_mfma_f32_16x16x32_bf16 v[84:87], v[184:187], v[222:225], v[84:87]
	v_mfma_f32_16x16x32_bf16 v[80:83], v[192:195], v[222:225], v[80:83]
	v_mfma_f32_16x16x32_bf16 v[68:71], v[184:187], v[230:233], v[68:71]
	v_mfma_f32_16x16x32_bf16 v[64:67], v[192:195], v[230:233], v[64:67]
	v_mfma_f32_16x16x32_bf16 v[116:119], v[188:191], v[210:213], v[116:119]
	v_mfma_f32_16x16x32_bf16 v[112:115], v[196:199], v[210:213], v[112:115]
	v_mfma_f32_16x16x32_bf16 v[100:103], v[188:191], v[218:221], v[100:103]
	v_mfma_f32_16x16x32_bf16 v[96:99], v[196:199], v[218:221], v[96:99]
	v_mfma_f32_16x16x32_bf16 v[84:87], v[188:191], v[226:229], v[84:87]
	v_mfma_f32_16x16x32_bf16 v[80:83], v[196:199], v[226:229], v[80:83]
	v_mfma_f32_16x16x32_bf16 v[68:71], v[188:191], v[234:237], v[68:71]
	v_mfma_f32_16x16x32_bf16 v[64:67], v[196:199], v[234:237], v[64:67]
	s_barrier
; #define PG8_STAGE(bufoff, gbase, voff) do { _Pragma("unroll") for (int _i = 0; _i < 2; ++_i) \
;         __builtin_amdgcn_global_load_lds((const unsigned*)((const char*)(gbase) + (voff)[_i]), (PG8_LAS unsigned*)(lds + (bufoff) + ldsw + _i * 8192), 16, 0, 0); } while (0)
; #define PG8_STAGEA(bufoff, gbase, voff) do { _Pragma("unroll") for (int _i = 0; _i < 2; ++_i) \
;         __builtin_amdgcn_global_load_lds((const unsigned*)((const char*)(gbase) + (voff)[_i]), (PG8_LAS unsigned*)(lds + (bufoff) + ldsw + _i * 8192), 16, 0, AUXA); } while (0)
; #define PG8_WAIT_V(n) asm volatile("s_waitcnt vmcnt(" #n ")" ::: "memory")
; #define PG8_WAIT_L(n) asm volatile("s_waitcnt lgkmcnt(" #n ")" ::: "memory")
; #define PG8_BAR __builtin_amdgcn_s_barrier()
;     ...
;             PG8_LDA(At, 1, 1); PG8_STAGE(PG8_SB(1, 0), b3, voffB); PG8_STAGE(PG8_SB(1, 1), b3 + hstepB, voffB); PG8_STAGEA(PG8_SA(1, 0), a3, voffA);
;             PG8_WAIT_V(8); PG8_WAIT_L(0); PG8_BAR; PG8_MMA(1, 0, At, B0); PG8_MMA(1, 1, At, B1); PG8_BAR; PG8_SCHED;
;             } else {
;             PG8_LDB(B0, 0, 0); PG8_SCHED; PG8_LDA(At, 0, 0); PG8_STAGEA(PG8_SA(1, 1), a1 + hstep, voffA);
;             PG8_WAIT_L(8); PG8_BAR; PG8_WAIT_L(0); PG8_MMA(0, 0, At, B0); PG8_BAR; PG8_SCHED;
;             PG8_LDB(B1, 0, 1); PG8_STAGE(PG8_SB(0, 0), b2, voffB);
;             PG8_BAR; PG8_WAIT_L(0); PG8_MMA(0, 1, At, B1); PG8_BAR;
;             PG8_LDA(At, 0, 1); PG8_STAGEA(PG8_SA(0, 0), a2, voffA);
;             PG8_BAR; PG8_WAIT_L(0); PG8_MMA(1, 0, At, B0); PG8_BAR; PG8_SCHED;
;             PG8_STAGE(PG8_SB(0, 1), b2 + hstepB, voffB);
;             PG8_WAIT_V(6); PG8_BAR; PG8_MMA(1, 1, At, B1); PG8_BAR;
;             PG8_LDB(B0, 1, 0); PG8_SCHED; PG8_LDA(At, 1, 0); PG8_STAGEA(PG8_SA(0, 1), a2 + hstep, voffA);
;             PG8_WAIT_L(8); PG8_BAR; PG8_WAIT_L(0); PG8_MMA(0, 0, At, B0); PG8_BAR; PG8_SCHED;
;             PG8_LDB(B1, 1, 1); PG8_STAGE(PG8_SB(1, 0), b3, voffB);
;             PG8_BAR; PG8_WAIT_L(0); PG8_MMA(0, 1, At, B1); PG8_BAR;
;             PG8_LDA(At, 1, 1); PG8_STAGEA(PG8_SA(1, 0), a3, voffA);
;             PG8_BAR; PG8_WAIT_L(0); PG8_MMA(1, 0, At, B0); PG8_BAR; PG8_SCHED;
;             PG8_STAGE(PG8_SB(1, 1), b3 + hstepB, voffB);
;             PG8_WAIT_V(6); PG8_BAR; PG8_MMA(1, 1, At, B1); PG8_BAR;
;             }
;         }
;         if constexpr (ALIGN_EPI) { if (wr == 0) PG8_BAR; }
	s_add_i32 s50, s74, s67
	v_lshl_add_u64 v[206:207], v[206:207], 0, s[16:17]
	s_mov_b32 m0, s50
	ds_read_b128 v[202:205], v164 offset:49152
	ds_read_b128 v[210:213], v164 offset:50176
	ds_read_b128 v[214:217], v164 offset:51200
	ds_read_b128 v[218:221], v164 offset:52224
	ds_read_b128 v[222:225], v164 offset:53248
	ds_read_b128 v[226:229], v164 offset:54272
	ds_read_b128 v[230:233], v164 offset:55296
	ds_read_b128 v[234:237], v164 offset:56320
	global_load_lds_dwordx4 v[206:207], off
	s_add_i32 m0, s50, 0x2000
	s_add_u32 s44, s44, 0x40080
	v_lshl_add_u64 v[206:207], v[238:239], 0, s[16:17]
	s_addc_u32 s45, s45, 0
	s_add_i32 s50, s75, s67
	global_load_lds_dwordx4 v[206:207], off
	v_lshl_add_u64 v[206:207], s[44:45], 0, v[136:137]
	s_mov_b32 m0, s50
	s_nop 0
	global_load_lds_dwordx4 v[206:207], off
	v_lshl_add_u64 v[206:207], s[44:45], 0, v[140:141]
	s_add_i32 m0, s50, 0x2000
	s_nop 0
	global_load_lds_dwordx4 v[206:207], off
	v_lshl_add_u64 v[206:207], v[240:241], 0, s[16:17]
	s_mov_b32 m0, s55
	s_nop 0
	global_load_lds_dwordx4 v[206:207], off
	v_lshl_add_u64 v[206:207], v[242:243], 0, s[16:17]
	s_mov_b32 m0, s56
	s_nop 0
	global_load_lds_dwordx4 v[206:207], off
	s_waitcnt vmcnt(8)
	s_waitcnt lgkmcnt(0)
	s_barrier
	s_waitcnt lgkmcnt(0)
	v_mfma_f32_16x16x32_bf16 v[60:63], v[166:169], v[202:205], v[60:63]
	v_mfma_f32_16x16x32_bf16 v[56:59], v[176:179], v[202:205], v[56:59]
	v_mfma_f32_16x16x32_bf16 v[44:47], v[166:169], v[214:217], v[44:47]
	v_mfma_f32_16x16x32_bf16 v[40:43], v[176:179], v[214:217], v[40:43]
	v_mfma_f32_16x16x32_bf16 v[28:31], v[166:169], v[222:225], v[28:31]
	v_mfma_f32_16x16x32_bf16 v[24:27], v[176:179], v[222:225], v[24:27]
	v_mfma_f32_16x16x32_bf16 v[12:15], v[166:169], v[230:233], v[12:15]
	v_mfma_f32_16x16x32_bf16 v[8:11], v[176:179], v[230:233], v[8:11]
	v_mfma_f32_16x16x32_bf16 v[60:63], v[170:173], v[210:213], v[60:63]
	v_mfma_f32_16x16x32_bf16 v[56:59], v[180:183], v[210:213], v[56:59]
	v_mfma_f32_16x16x32_bf16 v[44:47], v[170:173], v[218:221], v[44:47]
	v_mfma_f32_16x16x32_bf16 v[40:43], v[180:183], v[218:221], v[40:43]
	v_mfma_f32_16x16x32_bf16 v[28:31], v[170:173], v[226:229], v[28:31]
	v_mfma_f32_16x16x32_bf16 v[24:27], v[180:183], v[226:229], v[24:27]
	v_mfma_f32_16x16x32_bf16 v[12:15], v[170:173], v[234:237], v[12:15]
	v_mfma_f32_16x16x32_bf16 v[8:11], v[180:183], v[234:237], v[8:11]
	v_mfma_f32_16x16x32_bf16 v[52:55], v[184:187], v[202:205], v[52:55]
	v_mfma_f32_16x16x32_bf16 v[48:51], v[192:195], v[202:205], v[48:51]
	v_mfma_f32_16x16x32_bf16 v[36:39], v[184:187], v[214:217], v[36:39]
	v_mfma_f32_16x16x32_bf16 v[32:35], v[192:195], v[214:217], v[32:35]
	v_mfma_f32_16x16x32_bf16 v[20:23], v[184:187], v[222:225], v[20:23]
	v_mfma_f32_16x16x32_bf16 v[16:19], v[192:195], v[222:225], v[16:19]
	v_mfma_f32_16x16x32_bf16 v[4:7], v[184:187], v[230:233], v[4:7]
	v_mfma_f32_16x16x32_bf16 v[0:3], v[192:195], v[230:233], v[0:3]
	v_mfma_f32_16x16x32_bf16 v[52:55], v[188:191], v[210:213], v[52:55]
	v_mfma_f32_16x16x32_bf16 v[48:51], v[196:199], v[210:213], v[48:51]
	v_mfma_f32_16x16x32_bf16 v[36:39], v[188:191], v[218:221], v[36:39]
	v_mfma_f32_16x16x32_bf16 v[32:35], v[196:199], v[218:221], v[32:35]
	v_mfma_f32_16x16x32_bf16 v[20:23], v[188:191], v[226:229], v[20:23]
	v_mfma_f32_16x16x32_bf16 v[16:19], v[196:199], v[226:229], v[16:19]
	v_mfma_f32_16x16x32_bf16 v[4:7], v[188:191], v[234:237], v[4:7]
	v_mfma_f32_16x16x32_bf16 v[0:3], v[196:199], v[234:237], v[0:3]
	s_barrier
	s_add_i32 s44, s73, 2
	s_add_u32 s42, s42, 0x100
	s_addc_u32 s43, s43, 0
	v_lshl_add_u64 v[150:151], v[150:151], 0, s[20:21]
	v_lshl_add_u64 v[130:131], v[130:131], 0, s[20:21]
	s_cmp_ge_i32 s73, s57
	s_mov_b32 s73, s44
	s_cbranch_scc0 .LBB0_1054
	s_setprio 0
	s_and_b64 vcc, exec, s[18:19]
	s_cbranch_vccz .LBB0_1057
	s_barrier
